# select search: fold also to quarter-wave depth (8 registers) when the last key block fills lanes 0-15 only
# speedup vs baseline: 1.0127x; 1.0019x over previous
; __device__ __forceinline__ void select_query(const unsigned (&u)[64], unsigned vmax, int q, int b, int lane, unsigned* MASKb) {
;     const int n = q + 1, nblk = (n + 2047) >> 11;
;     unsigned T = 0u, TG = 0u; int rrem = 0;
;     if (n > 256) {
;         const unsigned kmax = wave_umax(vmax);
;         const unsigned K0 = 0x80000000u;
;         bool exact = false, done = false;
;         unsigned lo = 0u, hi = 0u; float Llo = 1.f, Lhi = 1.f;
;         const float L256 = 8.0028150156f;
;         const int cpos = count_ge(u, K0 + 1u, nblk);
.LBB0_130:
	v_add_u32_e32 v0, 0x800, v106
	v_ashrrev_i32_e32 v190, 11, v0
	s_mov_b64 s[8:9], exec
	v_mov_b32_e32 v192, 0
	v_mov_b32_e32 v193, 0
	v_mov_b32_e32 v191, 0
	s_cmpk_gt_i32 s75, 0xff
	s_cbranch_scc0 .Lsqa_done
	s_add_i32 s25, s75, 0x800
	s_lshr_b32 s25, s25, 11
	s_add_i32 s26, s75, 0
	s_and_b32 s26, s26, 0x7ff
	s_cmpk_lt_u32 s26, 0x400
	s_cselect_b32 s31, 1, 0
	s_cmpk_lt_u32 s26, 0x200
	s_addc_u32 s31, s31, 0
	s_mul_i32 s32, s25, 3
	s_sub_u32 s32, s32, s31
	s_cmp_eq_u32 s31, 0
	s_cbranch_scc1 .Lsqa_fon
	s_cmp_lt_u32 s32, 4
	s_cbranch_scc0 .Lsqa_fo1
	v_permlane32_swap_b32_e32 v138, v153
	v_permlane32_swap_b32_e32 v140, v156
	v_permlane32_swap_b32_e32 v139, v155
	v_permlane32_swap_b32_e32 v141, v157
	v_permlane32_swap_b32_e32 v142, v158
	v_permlane32_swap_b32_e32 v146, v160
	v_permlane32_swap_b32_e32 v143, v159
	v_permlane32_swap_b32_e32 v147, v161
	v_permlane32_swap_b32_e32 v144, v167
	v_permlane32_swap_b32_e32 v148, v169
	v_permlane32_swap_b32_e32 v145, v168
	v_permlane32_swap_b32_e32 v149, v170
	v_permlane32_swap_b32_e32 v150, v173
	v_permlane32_swap_b32_e32 v152, v174
	v_permlane32_swap_b32_e32 v151, v175
	v_permlane32_swap_b32_e32 v154, v176
	s_cmp_lt_u32 s31, 2
	s_cbranch_scc1 .Lsqa_fon
	v_permlane16_swap_b32_e32 v138, v144
	v_permlane16_swap_b32_e32 v140, v148
	v_permlane16_swap_b32_e32 v139, v145
	v_permlane16_swap_b32_e32 v141, v149
	v_permlane16_swap_b32_e32 v142, v150
	v_permlane16_swap_b32_e32 v146, v152
	v_permlane16_swap_b32_e32 v143, v151
	v_permlane16_swap_b32_e32 v147, v154
	s_branch .Lsqa_fon
.Lsqa_fo1:
	v_permlane32_swap_b32_e32 v76, v92
	v_permlane32_swap_b32_e32 v78, v95
	v_permlane32_swap_b32_e32 v77, v94
	v_permlane32_swap_b32_e32 v79, v96
	v_permlane32_swap_b32_e32 v80, v97
	v_permlane32_swap_b32_e32 v84, v172
	v_permlane32_swap_b32_e32 v81, v171
	v_permlane32_swap_b32_e32 v85, v178
	v_permlane32_swap_b32_e32 v82, v180
	v_permlane32_swap_b32_e32 v86, v183
	v_permlane32_swap_b32_e32 v83, v182
	v_permlane32_swap_b32_e32 v87, v184
	v_permlane32_swap_b32_e32 v89, v186
	v_permlane32_swap_b32_e32 v91, v187
	v_permlane32_swap_b32_e32 v90, v188
	v_permlane32_swap_b32_e32 v93, v189
	s_cmp_lt_u32 s31, 2
	s_cbranch_scc1 .Lsqa_fon
	v_permlane16_swap_b32_e32 v76, v82
	v_permlane16_swap_b32_e32 v78, v86
	v_permlane16_swap_b32_e32 v77, v83
	v_permlane16_swap_b32_e32 v79, v87
	v_permlane16_swap_b32_e32 v80, v89
	v_permlane16_swap_b32_e32 v84, v91
	v_permlane16_swap_b32_e32 v81, v90
	v_permlane16_swap_b32_e32 v85, v93

; __device__ __forceinline__ int count_ge(const unsigned (&u)[64], unsigned cand, int nblk) {
;     int c0 = 0, c1 = 0;
;     const unsigned ts = __builtin_amdgcn_readfirstlane(cand);
; #pragma unroll
;     for (int B = 0; B < 2; ++B) {
;         if (B < nblk) {
; #pragma unroll
;             for (int i = 0; i < 32; i += 4) CNT4(c0, c1, ts, u[B * 32 + i], u[B * 32 + i + 1], u[B * 32 + i + 2], u[B * 32 + i + 3]);
;         }
;     }
;     return wave_isum(c0 + c1);
; }
.Lsqa_count:
	v_mov_b32_e32 v0, 0
	v_mov_b32_e32 v34, 0
	v_cmp_le_u32_e64 s[4:5], s14, v138
	v_cmp_le_u32_e64 s[6:7], s14, v140
	v_cmp_le_u32_e64 s[10:11], s14, v139
	v_cmp_le_u32_e64 s[26:27], s14, v141
	v_addc_co_u32_e64 v0, s[28:29], 0, v0, s[4:5]
	v_addc_co_u32_e64 v34, s[30:31], 0, v34, s[6:7]
	v_addc_co_u32_e64 v0, s[28:29], 0, v0, s[10:11]
	v_addc_co_u32_e64 v34, s[30:31], 0, v34, s[26:27]
	v_cmp_le_u32_e64 s[4:5], s14, v142
	v_cmp_le_u32_e64 s[6:7], s14, v146
	v_cmp_le_u32_e64 s[10:11], s14, v143
	v_cmp_le_u32_e64 s[26:27], s14, v147
	v_addc_co_u32_e64 v0, s[28:29], 0, v0, s[4:5]
	v_addc_co_u32_e64 v34, s[30:31], 0, v34, s[6:7]
	v_addc_co_u32_e64 v0, s[28:29], 0, v0, s[10:11]
	v_addc_co_u32_e64 v34, s[30:31], 0, v34, s[26:27]
	s_cmp_eq_u32 s32, 1
	s_cbranch_scc1 .Lsqa_red
	v_cmp_le_u32_e64 s[4:5], s14, v144
	v_cmp_le_u32_e64 s[6:7], s14, v148
	v_cmp_le_u32_e64 s[10:11], s14, v145
	v_cmp_le_u32_e64 s[26:27], s14, v149
	v_addc_co_u32_e64 v0, s[28:29], 0, v0, s[4:5]
	v_addc_co_u32_e64 v34, s[30:31], 0, v34, s[6:7]
	v_addc_co_u32_e64 v0, s[28:29], 0, v0, s[10:11]
	v_addc_co_u32_e64 v34, s[30:31], 0, v34, s[26:27]
	v_cmp_le_u32_e64 s[4:5], s14, v150
	v_cmp_le_u32_e64 s[6:7], s14, v152
	v_cmp_le_u32_e64 s[10:11], s14, v151
	v_cmp_le_u32_e64 s[26:27], s14, v154
	v_addc_co_u32_e64 v0, s[28:29], 0, v0, s[4:5]
	v_addc_co_u32_e64 v34, s[30:31], 0, v34, s[6:7]
	v_addc_co_u32_e64 v0, s[28:29], 0, v0, s[10:11]
	v_addc_co_u32_e64 v34, s[30:31], 0, v34, s[26:27]
	s_cmp_eq_u32 s32, 2
	s_cbranch_scc1 .Lsqa_red
	v_cmp_le_u32_e64 s[4:5], s14, v153
	v_cmp_le_u32_e64 s[6:7], s14, v156
	v_cmp_le_u32_e64 s[10:11], s14, v155
	v_cmp_le_u32_e64 s[26:27], s14, v157
	v_addc_co_u32_e64 v0, s[28:29], 0, v0, s[4:5]
	v_addc_co_u32_e64 v34, s[30:31], 0, v34, s[6:7]
	v_addc_co_u32_e64 v0, s[28:29], 0, v0, s[10:11]
	v_addc_co_u32_e64 v34, s[30:31], 0, v34, s[26:27]
	v_cmp_le_u32_e64 s[4:5], s14, v158
	v_cmp_le_u32_e64 s[6:7], s14, v160
	v_cmp_le_u32_e64 s[10:11], s14, v159
	v_cmp_le_u32_e64 s[26:27], s14, v161
	v_addc_co_u32_e64 v0, s[28:29], 0, v0, s[4:5]
	v_addc_co_u32_e64 v34, s[30:31], 0, v34, s[6:7]
	v_addc_co_u32_e64 v0, s[28:29], 0, v0, s[10:11]
	v_addc_co_u32_e64 v34, s[30:31], 0, v34, s[26:27]
	v_cmp_le_u32_e64 s[4:5], s14, v167
	v_cmp_le_u32_e64 s[6:7], s14, v169
	v_cmp_le_u32_e64 s[10:11], s14, v168
	v_cmp_le_u32_e64 s[26:27], s14, v170
	v_addc_co_u32_e64 v0, s[28:29], 0, v0, s[4:5]
	v_addc_co_u32_e64 v34, s[30:31], 0, v34, s[6:7]
	v_addc_co_u32_e64 v0, s[28:29], 0, v0, s[10:11]
	v_addc_co_u32_e64 v34, s[30:31], 0, v34, s[26:27]
	v_cmp_le_u32_e64 s[4:5], s14, v173
	v_cmp_le_u32_e64 s[6:7], s14, v174
	v_cmp_le_u32_e64 s[10:11], s14, v175
	v_cmp_le_u32_e64 s[26:27], s14, v176
	v_addc_co_u32_e64 v0, s[28:29], 0, v0, s[4:5]
	v_addc_co_u32_e64 v34, s[30:31], 0, v34, s[6:7]
	v_addc_co_u32_e64 v0, s[28:29], 0, v0, s[10:11]
	v_addc_co_u32_e64 v34, s[30:31], 0, v34, s[26:27]
	s_cmp_eq_u32 s32, 3
	s_cbranch_scc1 .Lsqa_red
	v_cmp_le_u32_e64 s[4:5], s14, v76
	v_cmp_le_u32_e64 s[6:7], s14, v78
	v_cmp_le_u32_e64 s[10:11], s14, v77
	v_cmp_le_u32_e64 s[26:27], s14, v79
	v_addc_co_u32_e64 v0, s[28:29], 0, v0, s[4:5]
	v_addc_co_u32_e64 v34, s[30:31], 0, v34, s[6:7]
	v_addc_co_u32_e64 v0, s[28:29], 0, v0, s[10:11]
	v_addc_co_u32_e64 v34, s[30:31], 0, v34, s[26:27]
	v_cmp_le_u32_e64 s[4:5], s14, v80
	v_cmp_le_u32_e64 s[6:7], s14, v84
	v_cmp_le_u32_e64 s[10:11], s14, v81
	v_cmp_le_u32_e64 s[26:27], s14, v85
	v_addc_co_u32_e64 v0, s[28:29], 0, v0, s[4:5]
	v_addc_co_u32_e64 v34, s[30:31], 0, v34, s[6:7]
	v_addc_co_u32_e64 v0, s[28:29], 0, v0, s[10:11]
	v_addc_co_u32_e64 v34, s[30:31], 0, v34, s[26:27]
	s_cmp_eq_u32 s32, 4
	s_cbranch_scc1 .Lsqa_red
	v_cmp_le_u32_e64 s[4:5], s14, v82
	v_cmp_le_u32_e64 s[6:7], s14, v86
	v_cmp_le_u32_e64 s[10:11], s14, v83
	v_cmp_le_u32_e64 s[26:27], s14, v87
	v_addc_co_u32_e64 v0, s[28:29], 0, v0, s[4:5]
	v_addc_co_u32_e64 v34, s[30:31], 0, v34, s[6:7]
	v_addc_co_u32_e64 v0, s[28:29], 0, v0, s[10:11]
	v_addc_co_u32_e64 v34, s[30:31], 0, v34, s[26:27]
	v_cmp_le_u32_e64 s[4:5], s14, v89
	v_cmp_le_u32_e64 s[6:7], s14, v91
	v_cmp_le_u32_e64 s[10:11], s14, v90
	v_cmp_le_u32_e64 s[26:27], s14, v93
	v_addc_co_u32_e64 v0, s[28:29], 0, v0, s[4:5]
	v_addc_co_u32_e64 v34, s[30:31], 0, v34, s[6:7]
	v_addc_co_u32_e64 v0, s[28:29], 0, v0, s[10:11]
	v_addc_co_u32_e64 v34, s[30:31], 0, v34, s[26:27]
	s_cmp_eq_u32 s32, 5
	s_cbranch_scc1 .Lsqa_red
	v_cmp_le_u32_e64 s[4:5], s14, v92
	v_cmp_le_u32_e64 s[6:7], s14, v95
	v_cmp_le_u32_e64 s[10:11], s14, v94
	v_cmp_le_u32_e64 s[26:27], s14, v96
	v_addc_co_u32_e64 v0, s[28:29], 0, v0, s[4:5]
	v_addc_co_u32_e64 v34, s[30:31], 0, v34, s[6:7]
	v_addc_co_u32_e64 v0, s[28:29], 0, v0, s[10:11]
	v_addc_co_u32_e64 v34, s[30:31], 0, v34, s[26:27]
	v_cmp_le_u32_e64 s[4:5], s14, v97
	v_cmp_le_u32_e64 s[6:7], s14, v172
	v_cmp_le_u32_e64 s[10:11], s14, v171
	v_cmp_le_u32_e64 s[26:27], s14, v178
	v_addc_co_u32_e64 v0, s[28:29], 0, v0, s[4:5]
	v_addc_co_u32_e64 v34, s[30:31], 0, v34, s[6:7]
	v_addc_co_u32_e64 v0, s[28:29], 0, v0, s[10:11]
	v_addc_co_u32_e64 v34, s[30:31], 0, v34, s[26:27]
	v_cmp_le_u32_e64 s[4:5], s14, v180
	v_cmp_le_u32_e64 s[6:7], s14, v183
	v_cmp_le_u32_e64 s[10:11], s14, v182
	v_cmp_le_u32_e64 s[26:27], s14, v184
	v_addc_co_u32_e64 v0, s[28:29], 0, v0, s[4:5]
	v_addc_co_u32_e64 v34, s[30:31], 0, v34, s[6:7]
	v_addc_co_u32_e64 v0, s[28:29], 0, v0, s[10:11]
	v_addc_co_u32_e64 v34, s[30:31], 0, v34, s[26:27]
	v_cmp_le_u32_e64 s[4:5], s14, v186
	v_cmp_le_u32_e64 s[6:7], s14, v187
	v_cmp_le_u32_e64 s[10:11], s14, v188
	v_cmp_le_u32_e64 s[26:27], s14, v189
	v_addc_co_u32_e64 v0, s[28:29], 0, v0, s[4:5]
	v_addc_co_u32_e64 v34, s[30:31], 0, v34, s[6:7]
	v_addc_co_u32_e64 v0, s[28:29], 0, v0, s[10:11]
	v_addc_co_u32_e64 v34, s[30:31], 0, v34, s[26:27]

; __device__ __forceinline__ void select_query(const unsigned (&u)[64], unsigned vmax, int q, int b, int lane, unsigned* MASKb) {
;     ...
;         if (exact) TG = T - 1u; else { TG = T; rrem = 256 - count_ge(u, T + 1u, nblk); }
;     }
;     int tbase = 0;
; #pragma unroll
;     for (int B = 0; B < 2; ++B) {
;         if (B < nblk) {
;             unsigned w = 0u; const unsigned tgs = __builtin_amdgcn_readfirstlane(TG);
; #pragma unroll
;             for (int e = 31; e >= 3; e -= 4) BIT4(w, tgs, u[B * 32 + e], u[B * 32 + e - 1], u[B * 32 + e - 2], u[B * 32 + e - 3]);
.Lsqa_fin:
	s_mul_i32 s31, s25, 3
	s_sub_u32 s31, s31, s32
	s_cmp_eq_u32 s31, 0
	s_cbranch_scc1 .Lsqa_unn
	s_cmp_lt_u32 s32, 4
	s_cbranch_scc0 .Lsqa_un1
	s_cmp_lt_u32 s31, 2
	s_cbranch_scc1 .Lsqa_un0a
	v_permlane16_swap_b32_e32 v138, v144
	v_permlane16_swap_b32_e32 v140, v148
	v_permlane16_swap_b32_e32 v139, v145
	v_permlane16_swap_b32_e32 v141, v149
	v_permlane16_swap_b32_e32 v142, v150
	v_permlane16_swap_b32_e32 v146, v152
	v_permlane16_swap_b32_e32 v143, v151
	v_permlane16_swap_b32_e32 v147, v154
.Lsqa_un0a:
	v_permlane32_swap_b32_e32 v138, v153
	v_permlane32_swap_b32_e32 v140, v156
	v_permlane32_swap_b32_e32 v139, v155
	v_permlane32_swap_b32_e32 v141, v157
	v_permlane32_swap_b32_e32 v142, v158
	v_permlane32_swap_b32_e32 v146, v160
	v_permlane32_swap_b32_e32 v143, v159
	v_permlane32_swap_b32_e32 v147, v161
	v_permlane32_swap_b32_e32 v144, v167
	v_permlane32_swap_b32_e32 v148, v169
	v_permlane32_swap_b32_e32 v145, v168
	v_permlane32_swap_b32_e32 v149, v170
	v_permlane32_swap_b32_e32 v150, v173
	v_permlane32_swap_b32_e32 v152, v174
	v_permlane32_swap_b32_e32 v151, v175
	v_permlane32_swap_b32_e32 v154, v176
	s_branch .Lsqa_unn
.Lsqa_un1:
	s_cmp_lt_u32 s31, 2
	s_cbranch_scc1 .Lsqa_un1a
	v_permlane16_swap_b32_e32 v76, v82
	v_permlane16_swap_b32_e32 v78, v86
	v_permlane16_swap_b32_e32 v77, v83
	v_permlane16_swap_b32_e32 v79, v87
	v_permlane16_swap_b32_e32 v80, v89
	v_permlane16_swap_b32_e32 v84, v91
	v_permlane16_swap_b32_e32 v81, v90
	v_permlane16_swap_b32_e32 v85, v93

; __device__ __forceinline__ void select_query(const unsigned (&u)[64], unsigned vmax, int q, int b, int lane, unsigned* MASKb) {
;     const int n = q + 1, nblk = (n + 2047) >> 11;
;     unsigned T = 0u, TG = 0u; int rrem = 0;
;     if (n > 256) {
;         const unsigned kmax = wave_umax(vmax);
;         const unsigned K0 = 0x80000000u;
;         bool exact = false, done = false;
;         unsigned lo = 0u, hi = 0u; float Llo = 1.f, Lhi = 1.f;
;         const float L256 = 8.0028150156f;
;         const int cpos = count_ge(u, K0 + 1u, nblk);
.LBB0_184:
	s_or_b64 exec, exec, s[70:71]
	v_add_u32_e32 v0, 0x801, v106
	v_ashrrev_i32_e32 v0, 11, v0
	s_mov_b64 s[8:9], exec
	v_mov_b32_e32 v76, 0
	v_mov_b32_e32 v77, 0
	v_mov_b32_e32 v69, 0
	s_cmpk_gt_i32 s75, 0xfe
	s_cbranch_scc0 .Lsqb_done
	s_add_i32 s25, s75, 0x801
	s_lshr_b32 s25, s25, 11
	s_add_i32 s26, s75, 1
	s_and_b32 s26, s26, 0x7ff
	s_cmpk_lt_u32 s26, 0x400
	s_cselect_b32 s31, 1, 0
	s_cmpk_lt_u32 s26, 0x200
	s_addc_u32 s31, s31, 0
	s_mul_i32 s32, s25, 3
	s_sub_u32 s32, s32, s31
	s_cmp_eq_u32 s31, 0
	s_cbranch_scc1 .Lsqb_fon
	s_cmp_lt_u32 s32, 4
	s_cbranch_scc0 .Lsqb_fo1
	v_permlane32_swap_b32_e32 v98, v120
	v_permlane32_swap_b32_e32 v107, v123
	v_permlane32_swap_b32_e32 v99, v122
	v_permlane32_swap_b32_e32 v108, v124
	v_permlane32_swap_b32_e32 v109, v125
	v_permlane32_swap_b32_e32 v113, v127
	v_permlane32_swap_b32_e32 v110, v126
	v_permlane32_swap_b32_e32 v114, v128
	v_permlane32_swap_b32_e32 v111, v129
	v_permlane32_swap_b32_e32 v115, v131
	v_permlane32_swap_b32_e32 v112, v130
	v_permlane32_swap_b32_e32 v116, v132
	v_permlane32_swap_b32_e32 v117, v133
	v_permlane32_swap_b32_e32 v119, v134
	v_permlane32_swap_b32_e32 v118, v136
	v_permlane32_swap_b32_e32 v121, v137
	s_cmp_lt_u32 s31, 2
	s_cbranch_scc1 .Lsqb_fon
	v_permlane16_swap_b32_e32 v98, v111
	v_permlane16_swap_b32_e32 v107, v115
	v_permlane16_swap_b32_e32 v99, v112
	v_permlane16_swap_b32_e32 v108, v116
	v_permlane16_swap_b32_e32 v109, v117
	v_permlane16_swap_b32_e32 v113, v119
	v_permlane16_swap_b32_e32 v110, v118
	v_permlane16_swap_b32_e32 v114, v121
	s_branch .Lsqb_fon
.Lsqb_fo1:
	v_permlane32_swap_b32_e32 v46, v53
	v_permlane32_swap_b32_e32 v48, v56
	v_permlane32_swap_b32_e32 v47, v55
	v_permlane32_swap_b32_e32 v49, v57
	v_permlane32_swap_b32_e32 v42, v58
	v_permlane32_swap_b32_e32 v50, v60
	v_permlane32_swap_b32_e32 v43, v59
	v_permlane32_swap_b32_e32 v44, v61
	v_permlane32_swap_b32_e32 v38, v62
	v_permlane32_swap_b32_e32 v45, v64
	v_permlane32_swap_b32_e32 v39, v63
	v_permlane32_swap_b32_e32 v40, v65
	v_permlane32_swap_b32_e32 v41, v72
	v_permlane32_swap_b32_e32 v52, v73
	v_permlane32_swap_b32_e32 v51, v74
	v_permlane32_swap_b32_e32 v54, v75
	s_cmp_lt_u32 s31, 2
	s_cbranch_scc1 .Lsqb_fon
	v_permlane16_swap_b32_e32 v46, v38
	v_permlane16_swap_b32_e32 v48, v45
	v_permlane16_swap_b32_e32 v47, v39
	v_permlane16_swap_b32_e32 v49, v40
	v_permlane16_swap_b32_e32 v42, v41
	v_permlane16_swap_b32_e32 v50, v52
	v_permlane16_swap_b32_e32 v43, v51
	v_permlane16_swap_b32_e32 v44, v54

; __device__ __forceinline__ int count_ge(const unsigned (&u)[64], unsigned cand, int nblk) {
;     int c0 = 0, c1 = 0;
;     const unsigned ts = __builtin_amdgcn_readfirstlane(cand);
; #pragma unroll
;     for (int B = 0; B < 2; ++B) {
;         if (B < nblk) {
; #pragma unroll
;             for (int i = 0; i < 32; i += 4) CNT4(c0, c1, ts, u[B * 32 + i], u[B * 32 + i + 1], u[B * 32 + i + 2], u[B * 32 + i + 3]);
;         }
;     }
;     return wave_isum(c0 + c1);
; }
.Lsqb_count:
	v_mov_b32_e32 v138, 0
	v_mov_b32_e32 v140, 0
	v_cmp_le_u32_e64 s[4:5], s14, v98
	v_cmp_le_u32_e64 s[6:7], s14, v107
	v_cmp_le_u32_e64 s[10:11], s14, v99
	v_cmp_le_u32_e64 s[26:27], s14, v108
	v_addc_co_u32_e64 v138, s[28:29], 0, v138, s[4:5]
	v_addc_co_u32_e64 v140, s[30:31], 0, v140, s[6:7]
	v_addc_co_u32_e64 v138, s[28:29], 0, v138, s[10:11]
	v_addc_co_u32_e64 v140, s[30:31], 0, v140, s[26:27]
	v_cmp_le_u32_e64 s[4:5], s14, v109
	v_cmp_le_u32_e64 s[6:7], s14, v113
	v_cmp_le_u32_e64 s[10:11], s14, v110
	v_cmp_le_u32_e64 s[26:27], s14, v114
	v_addc_co_u32_e64 v138, s[28:29], 0, v138, s[4:5]
	v_addc_co_u32_e64 v140, s[30:31], 0, v140, s[6:7]
	v_addc_co_u32_e64 v138, s[28:29], 0, v138, s[10:11]
	v_addc_co_u32_e64 v140, s[30:31], 0, v140, s[26:27]
	s_cmp_eq_u32 s32, 1
	s_cbranch_scc1 .Lsqb_red
	v_cmp_le_u32_e64 s[4:5], s14, v111
	v_cmp_le_u32_e64 s[6:7], s14, v115
	v_cmp_le_u32_e64 s[10:11], s14, v112
	v_cmp_le_u32_e64 s[26:27], s14, v116
	v_addc_co_u32_e64 v138, s[28:29], 0, v138, s[4:5]
	v_addc_co_u32_e64 v140, s[30:31], 0, v140, s[6:7]
	v_addc_co_u32_e64 v138, s[28:29], 0, v138, s[10:11]
	v_addc_co_u32_e64 v140, s[30:31], 0, v140, s[26:27]
	v_cmp_le_u32_e64 s[4:5], s14, v117
	v_cmp_le_u32_e64 s[6:7], s14, v119
	v_cmp_le_u32_e64 s[10:11], s14, v118
	v_cmp_le_u32_e64 s[26:27], s14, v121
	v_addc_co_u32_e64 v138, s[28:29], 0, v138, s[4:5]
	v_addc_co_u32_e64 v140, s[30:31], 0, v140, s[6:7]
	v_addc_co_u32_e64 v138, s[28:29], 0, v138, s[10:11]
	v_addc_co_u32_e64 v140, s[30:31], 0, v140, s[26:27]
	s_cmp_eq_u32 s32, 2
	s_cbranch_scc1 .Lsqb_red
	v_cmp_le_u32_e64 s[4:5], s14, v120
	v_cmp_le_u32_e64 s[6:7], s14, v123
	v_cmp_le_u32_e64 s[10:11], s14, v122
	v_cmp_le_u32_e64 s[26:27], s14, v124
	v_addc_co_u32_e64 v138, s[28:29], 0, v138, s[4:5]
	v_addc_co_u32_e64 v140, s[30:31], 0, v140, s[6:7]
	v_addc_co_u32_e64 v138, s[28:29], 0, v138, s[10:11]
	v_addc_co_u32_e64 v140, s[30:31], 0, v140, s[26:27]
	v_cmp_le_u32_e64 s[4:5], s14, v125
	v_cmp_le_u32_e64 s[6:7], s14, v127
	v_cmp_le_u32_e64 s[10:11], s14, v126
	v_cmp_le_u32_e64 s[26:27], s14, v128
	v_addc_co_u32_e64 v138, s[28:29], 0, v138, s[4:5]
	v_addc_co_u32_e64 v140, s[30:31], 0, v140, s[6:7]
	v_addc_co_u32_e64 v138, s[28:29], 0, v138, s[10:11]
	v_addc_co_u32_e64 v140, s[30:31], 0, v140, s[26:27]
	v_cmp_le_u32_e64 s[4:5], s14, v129
	v_cmp_le_u32_e64 s[6:7], s14, v131
	v_cmp_le_u32_e64 s[10:11], s14, v130
	v_cmp_le_u32_e64 s[26:27], s14, v132
	v_addc_co_u32_e64 v138, s[28:29], 0, v138, s[4:5]
	v_addc_co_u32_e64 v140, s[30:31], 0, v140, s[6:7]
	v_addc_co_u32_e64 v138, s[28:29], 0, v138, s[10:11]
	v_addc_co_u32_e64 v140, s[30:31], 0, v140, s[26:27]
	v_cmp_le_u32_e64 s[4:5], s14, v133
	v_cmp_le_u32_e64 s[6:7], s14, v134
	v_cmp_le_u32_e64 s[10:11], s14, v136
	v_cmp_le_u32_e64 s[26:27], s14, v137
	v_addc_co_u32_e64 v138, s[28:29], 0, v138, s[4:5]
	v_addc_co_u32_e64 v140, s[30:31], 0, v140, s[6:7]
	v_addc_co_u32_e64 v138, s[28:29], 0, v138, s[10:11]
	v_addc_co_u32_e64 v140, s[30:31], 0, v140, s[26:27]
	s_cmp_eq_u32 s32, 3
	s_cbranch_scc1 .Lsqb_red
	v_cmp_le_u32_e64 s[4:5], s14, v46
	v_cmp_le_u32_e64 s[6:7], s14, v48
	v_cmp_le_u32_e64 s[10:11], s14, v47
	v_cmp_le_u32_e64 s[26:27], s14, v49
	v_addc_co_u32_e64 v138, s[28:29], 0, v138, s[4:5]
	v_addc_co_u32_e64 v140, s[30:31], 0, v140, s[6:7]
	v_addc_co_u32_e64 v138, s[28:29], 0, v138, s[10:11]
	v_addc_co_u32_e64 v140, s[30:31], 0, v140, s[26:27]
	v_cmp_le_u32_e64 s[4:5], s14, v42
	v_cmp_le_u32_e64 s[6:7], s14, v50
	v_cmp_le_u32_e64 s[10:11], s14, v43
	v_cmp_le_u32_e64 s[26:27], s14, v44
	v_addc_co_u32_e64 v138, s[28:29], 0, v138, s[4:5]
	v_addc_co_u32_e64 v140, s[30:31], 0, v140, s[6:7]
	v_addc_co_u32_e64 v138, s[28:29], 0, v138, s[10:11]
	v_addc_co_u32_e64 v140, s[30:31], 0, v140, s[26:27]
	s_cmp_eq_u32 s32, 4
	s_cbranch_scc1 .Lsqb_red
	v_cmp_le_u32_e64 s[4:5], s14, v38
	v_cmp_le_u32_e64 s[6:7], s14, v45
	v_cmp_le_u32_e64 s[10:11], s14, v39
	v_cmp_le_u32_e64 s[26:27], s14, v40
	v_addc_co_u32_e64 v138, s[28:29], 0, v138, s[4:5]
	v_addc_co_u32_e64 v140, s[30:31], 0, v140, s[6:7]
	v_addc_co_u32_e64 v138, s[28:29], 0, v138, s[10:11]
	v_addc_co_u32_e64 v140, s[30:31], 0, v140, s[26:27]
	v_cmp_le_u32_e64 s[4:5], s14, v41
	v_cmp_le_u32_e64 s[6:7], s14, v52
	v_cmp_le_u32_e64 s[10:11], s14, v51
	v_cmp_le_u32_e64 s[26:27], s14, v54
	v_addc_co_u32_e64 v138, s[28:29], 0, v138, s[4:5]
	v_addc_co_u32_e64 v140, s[30:31], 0, v140, s[6:7]
	v_addc_co_u32_e64 v138, s[28:29], 0, v138, s[10:11]
	v_addc_co_u32_e64 v140, s[30:31], 0, v140, s[26:27]
	s_cmp_eq_u32 s32, 5
	s_cbranch_scc1 .Lsqb_red
	v_cmp_le_u32_e64 s[4:5], s14, v53
	v_cmp_le_u32_e64 s[6:7], s14, v56
	v_cmp_le_u32_e64 s[10:11], s14, v55
	v_cmp_le_u32_e64 s[26:27], s14, v57
	v_addc_co_u32_e64 v138, s[28:29], 0, v138, s[4:5]
	v_addc_co_u32_e64 v140, s[30:31], 0, v140, s[6:7]
	v_addc_co_u32_e64 v138, s[28:29], 0, v138, s[10:11]
	v_addc_co_u32_e64 v140, s[30:31], 0, v140, s[26:27]
	v_cmp_le_u32_e64 s[4:5], s14, v58
	v_cmp_le_u32_e64 s[6:7], s14, v60
	v_cmp_le_u32_e64 s[10:11], s14, v59
	v_cmp_le_u32_e64 s[26:27], s14, v61
	v_addc_co_u32_e64 v138, s[28:29], 0, v138, s[4:5]
	v_addc_co_u32_e64 v140, s[30:31], 0, v140, s[6:7]
	v_addc_co_u32_e64 v138, s[28:29], 0, v138, s[10:11]
	v_addc_co_u32_e64 v140, s[30:31], 0, v140, s[26:27]
	v_cmp_le_u32_e64 s[4:5], s14, v62
	v_cmp_le_u32_e64 s[6:7], s14, v64
	v_cmp_le_u32_e64 s[10:11], s14, v63
	v_cmp_le_u32_e64 s[26:27], s14, v65
	v_addc_co_u32_e64 v138, s[28:29], 0, v138, s[4:5]
	v_addc_co_u32_e64 v140, s[30:31], 0, v140, s[6:7]
	v_addc_co_u32_e64 v138, s[28:29], 0, v138, s[10:11]
	v_addc_co_u32_e64 v140, s[30:31], 0, v140, s[26:27]
	v_cmp_le_u32_e64 s[4:5], s14, v72
	v_cmp_le_u32_e64 s[6:7], s14, v73
	v_cmp_le_u32_e64 s[10:11], s14, v74
	v_cmp_le_u32_e64 s[26:27], s14, v75
	v_addc_co_u32_e64 v138, s[28:29], 0, v138, s[4:5]
	v_addc_co_u32_e64 v140, s[30:31], 0, v140, s[6:7]
	v_addc_co_u32_e64 v138, s[28:29], 0, v138, s[10:11]
	v_addc_co_u32_e64 v140, s[30:31], 0, v140, s[26:27]

; __device__ __forceinline__ void select_query(const unsigned (&u)[64], unsigned vmax, int q, int b, int lane, unsigned* MASKb) {
;     ...
;         if (exact) TG = T - 1u; else { TG = T; rrem = 256 - count_ge(u, T + 1u, nblk); }
;     }
;     int tbase = 0;
; #pragma unroll
;     for (int B = 0; B < 2; ++B) {
;         if (B < nblk) {
;             unsigned w = 0u; const unsigned tgs = __builtin_amdgcn_readfirstlane(TG);
; #pragma unroll
;             for (int e = 31; e >= 3; e -= 4) BIT4(w, tgs, u[B * 32 + e], u[B * 32 + e - 1], u[B * 32 + e - 2], u[B * 32 + e - 3]);
.Lsqb_fin:
	s_mul_i32 s31, s25, 3
	s_sub_u32 s31, s31, s32
	s_cmp_eq_u32 s31, 0
	s_cbranch_scc1 .Lsqb_unn
	s_cmp_lt_u32 s32, 4
	s_cbranch_scc0 .Lsqb_un1
	s_cmp_lt_u32 s31, 2
	s_cbranch_scc1 .Lsqb_un0a
	v_permlane16_swap_b32_e32 v98, v111
	v_permlane16_swap_b32_e32 v107, v115
	v_permlane16_swap_b32_e32 v99, v112
	v_permlane16_swap_b32_e32 v108, v116
	v_permlane16_swap_b32_e32 v109, v117
	v_permlane16_swap_b32_e32 v113, v119
	v_permlane16_swap_b32_e32 v110, v118
	v_permlane16_swap_b32_e32 v114, v121
.Lsqb_un0a:
	v_permlane32_swap_b32_e32 v98, v120
	v_permlane32_swap_b32_e32 v107, v123
	v_permlane32_swap_b32_e32 v99, v122
	v_permlane32_swap_b32_e32 v108, v124
	v_permlane32_swap_b32_e32 v109, v125
	v_permlane32_swap_b32_e32 v113, v127
	v_permlane32_swap_b32_e32 v110, v126
	v_permlane32_swap_b32_e32 v114, v128
	v_permlane32_swap_b32_e32 v111, v129
	v_permlane32_swap_b32_e32 v115, v131
	v_permlane32_swap_b32_e32 v112, v130
	v_permlane32_swap_b32_e32 v116, v132
	v_permlane32_swap_b32_e32 v117, v133
	v_permlane32_swap_b32_e32 v119, v134
	v_permlane32_swap_b32_e32 v118, v136
	v_permlane32_swap_b32_e32 v121, v137
	s_branch .Lsqb_unn
.Lsqb_un1:
	s_cmp_lt_u32 s31, 2
	s_cbranch_scc1 .Lsqb_un1a
	v_permlane16_swap_b32_e32 v46, v38
	v_permlane16_swap_b32_e32 v48, v45
	v_permlane16_swap_b32_e32 v47, v39
	v_permlane16_swap_b32_e32 v49, v40
	v_permlane16_swap_b32_e32 v42, v41
	v_permlane16_swap_b32_e32 v50, v52
	v_permlane16_swap_b32_e32 v43, v51
	v_permlane16_swap_b32_e32 v44, v54
